# grid barrier: L1 invalidate issued at arrival, last arriver releases all XCD generation words directly (one hop fewer)
# speedup vs baseline: 1.0102x; 1.0102x over previous
; __device__ __forceinline__ unsigned xb_ld(unsigned* p)              { return __hip_atomic_load(p, __ATOMIC_RELAXED, __HIP_MEMORY_SCOPE_AGENT); }
; __device__ __forceinline__ void xcd_barrier_complete(unsigned* bar, unsigned x, unsigned& nloc, unsigned& nx) {
;     const unsigned G = gridDim.x * gridDim.y * gridDim.z;
;     unsigned sum, cnt, mine, sp = 0u;
;     for (;;) {
;         sum = 0u; cnt = 0u; mine = 0u;
; #pragma unroll
;         for (unsigned j = 0; j < 16; ++j) { const unsigned c = xb_ld(&bar[XB_XCNT(j)]); sum += c; cnt += (c > 0u) ? 1u : 0u; mine = (j == x) ? c : mine; }
; __device__ __forceinline__ void xcd_barrier(const XcdBarrier& b) {
;     asm volatile("s_waitcnt vmcnt(0)" ::: "memory");
;     __syncthreads();
;     if (threadIdx.x == 0) {
;         unsigned* bar = b.bar;
;         __builtin_amdgcn_s_waitcnt(0);
;         unsigned nloc = b.st[0], nx = b.st[1];
;         if (nloc == 0u) { xcd_barrier_complete(bar, b.x, nloc, nx); b.st[0] = nloc; b.st[1] = nx; }
.LBB0_77:
	s_cmp_gt_i32 s25, 1
	s_cselect_b64 s[0:1], -1, 0
	s_and_b64 s[2:3], s[6:7], s[0:1]
	s_andn2_b64 vcc, exec, s[2:3]
	s_cbranch_vccnz .LBB0_131
	s_waitcnt vmcnt(0)
	s_waitcnt lgkmcnt(0)
	s_barrier
	s_mov_b64 s[2:3], exec
	v_readlane_b32 s4, v246, 4
	v_readlane_b32 s5, v246, 5
	s_and_b64 s[4:5], s[2:3], s[4:5]
	s_mov_b64 exec, s[4:5]
	s_cbranch_execz .LBB0_130
	s_add_i32 s4, 0, 0x20020
	v_mov_b32_e32 v0, s4
	s_waitcnt vmcnt(0) expcnt(0) lgkmcnt(0)
	buffer_inv sc1
	ds_read_b32 v2, v0
	s_add_i32 s4, 0, 0x20024
	v_mov_b32_e32 v0, s4
	ds_read_b32 v0, v0
	s_waitcnt lgkmcnt(1)
	v_cmp_ne_u32_e32 vcc, 0, v2
	s_cbranch_vccnz .LBB0_94
	v_readlane_b32 s4, v246, 0
	s_mul_i32 s14, s27, s4
	s_add_u32 s4, s22, 0x80200
	s_addc_u32 s5, s23, 0
	s_add_u32 s6, s22, 0x80400
	s_addc_u32 s7, s23, 0
	s_add_u32 s28, s22, 0x80500
	s_addc_u32 s29, s23, 0
	s_add_u32 s30, s22, 0x80600
	s_addc_u32 s31, s23, 0
	s_add_u32 s34, s22, 0x80700
	s_addc_u32 s35, s23, 0
	s_add_u32 s36, s22, 0x80800
	s_addc_u32 s37, s23, 0
	s_add_u32 s38, s22, 0x80900
	s_addc_u32 s39, s23, 0
	s_add_u32 s40, s22, 0x80a00
	s_addc_u32 s41, s23, 0
	s_add_u32 s52, s22, 0x80b00
	s_addc_u32 s53, s23, 0
	s_add_u32 s54, s22, 0x80c00
	s_addc_u32 s55, s23, 0
	s_add_u32 s56, s22, 0x80d00
	s_addc_u32 s57, s23, 0
	s_add_u32 s58, s22, 0x80e00
	s_addc_u32 s59, s23, 0
	s_add_u32 s60, s22, 0x80f00
	s_addc_u32 s61, s23, 0
	s_add_u32 s62, s22, 0x81000
	s_addc_u32 s63, s23, 0
	s_add_u32 s68, s22, 0x81100
	s_addc_u32 s69, s23, 0
	s_add_u32 s70, s22, 0x81200
	s_addc_u32 s71, s23, 0
	s_add_u32 s72, s22, 0x81300
	s_mul_i32 s14, s14, s26
	s_addc_u32 s73, s23, 0
	s_mov_b32 s15, 1
	v_mov_b32_e32 v16, 0
	s_branch .LBB0_82

; __device__ __forceinline__ unsigned xb_ld(unsigned* p)              { return __hip_atomic_load(p, __ATOMIC_RELAXED, __HIP_MEMORY_SCOPE_AGENT); }
; __device__ __forceinline__ unsigned xb_add(unsigned* p, unsigned v) { return __hip_atomic_fetch_add(p, v, __ATOMIC_RELAXED, __HIP_MEMORY_SCOPE_AGENT); }
; #define XB_SPIN(cond, bar) do { unsigned _sp = 0; while (cond) { __builtin_amdgcn_s_sleep(1); \
;     if ((++_sp & 255u) == 0u) { if (xb_ld(&(bar)[XB_TMO])) break; if (_sp > XB_SPIN_CAP) { atomicAdd(&(bar)[XB_TMO], 1u); break; } } } } while (0)
; __device__ __forceinline__ void xcd_barrier(const XcdBarrier& b) {
;     ...
;         const unsigned old = xb_add(&bar[XB_XSUB(b.x)], 1u);
;         const unsigned gen = old / nloc;
;         if (old + 1u == (gen + 1u) * nloc) {
;             __builtin_amdgcn_fence(__ATOMIC_RELEASE, "agent");
;             asm volatile("s_waitcnt vmcnt(0)" ::: "memory");
;             const unsigned og = xb_add(&bar[XB_TOP], 1u);
;             const unsigned tg = og / nx;
;             if (og + 1u == (tg + 1u) * nx) xb_add(&bar[XB_TOPGEN], 1u);
;             else XB_SPIN(xb_ld(&bar[XB_TOPGEN]) == tg, bar);
;             __builtin_amdgcn_fence(__ATOMIC_ACQUIRE, "agent");
;             xb_add(&bar[XB_XGEN(b.x)], 1u);
;             asm volatile("s_waitcnt vmcnt(0)" ::: "memory");
;         } else {
;             XB_SPIN(xb_ld(&bar[XB_XGEN(b.x)]) == gen, bar);
;             __builtin_amdgcn_fence(__ATOMIC_ACQUIRE, "agent");
;             asm volatile("s_waitcnt vmcnt(0)" ::: "memory");
;         }
.LBB0_94:
	s_waitcnt lgkmcnt(0)
	v_readlane_b32 s15, v246, 3
	v_readlane_b32 s8, v246, 1
	v_readlane_b32 s9, v246, 2
	v_mov_b32_e32 v3, 0x1400
	v_mov_b32_e32 v4, 1
	s_lshl_b32 s15, s15, 8
	s_add_u32 s38, s8, s15
	s_addc_u32 s39, s9, 0
	s_add_u32 s40, s8, 0x200
	s_addc_u32 s41, s9, 0
	v_cvt_f32_u32_e32 v6, v2
	v_sub_u32_e32 v7, 0, v2
	global_atomic_add v5, v3, v4, s[38:39] sc0
	v_rcp_iflag_f32_e32 v6, v6
	v_mov_b32_e32 v10, 0
	v_mul_f32_e32 v6, 0x4f7ffffe, v6
	v_cvt_u32_f32_e32 v6, v6
	v_mul_lo_u32 v7, v7, v6
	v_mul_hi_u32 v7, v6, v7
	v_add_u32_e32 v6, v6, v7
	s_waitcnt vmcnt(0)
	v_mul_hi_u32 v1, v5, v6
	v_mul_lo_u32 v7, v1, v2
	v_sub_u32_e32 v7, v5, v7
	v_add_u32_e32 v8, 1, v1
	v_cmp_ge_u32_e32 vcc, v7, v2
	s_nop 1
	v_cndmask_b32_e32 v1, v1, v8, vcc
	v_sub_u32_e32 v8, v7, v2
	v_cndmask_b32_e32 v7, v7, v8, vcc
	v_add_u32_e32 v8, 1, v1
	v_cmp_ge_u32_e32 vcc, v7, v2
	v_add_u32_e32 v9, 1, v5
	s_nop 0
	v_cndmask_b32_e32 v1, v1, v8, vcc
	v_add_u32_e32 v8, 1, v1
	v_mul_lo_u32 v7, v8, v2
	v_cmp_ne_u32_e32 vcc, v9, v7
	s_cbranch_vccnz .Lxb_wait_0
	buffer_wbl2 sc1
	v_mov_b32_e32 v3, 0x3400
	s_waitcnt vmcnt(0)
	global_atomic_add v5, v3, v4, s[8:9] sc0
	v_mul_lo_u32 v7, v8, v0
	s_waitcnt vmcnt(0)
	v_add_u32_e32 v9, 1, v5
	v_cmp_ne_u32_e32 vcc, v9, v7
	s_cbranch_vccnz .Lxb_wait_0
	v_mov_b32_e32 v3, 0x2400
	global_atomic_add v3, v4, s[8:9]
	v_mov_b32_e32 v3, 0x2500
	global_atomic_add v3, v4, s[8:9]
	v_mov_b32_e32 v3, 0x2600
	global_atomic_add v3, v4, s[8:9]
	v_mov_b32_e32 v3, 0x2700
	global_atomic_add v3, v4, s[8:9]
	v_mov_b32_e32 v3, 0x2800
	global_atomic_add v3, v4, s[8:9]
	v_mov_b32_e32 v3, 0x2900
	global_atomic_add v3, v4, s[8:9]
	v_mov_b32_e32 v3, 0x2a00
	global_atomic_add v3, v4, s[8:9]
	v_mov_b32_e32 v3, 0x2b00
	global_atomic_add v3, v4, s[8:9]
	v_mov_b32_e32 v3, 0x2c00
	global_atomic_add v3, v4, s[8:9]
	v_mov_b32_e32 v3, 0x2d00
	global_atomic_add v3, v4, s[8:9]
	v_mov_b32_e32 v3, 0x2e00
	global_atomic_add v3, v4, s[8:9]
	v_mov_b32_e32 v3, 0x2f00
	global_atomic_add v3, v4, s[8:9]
	v_mov_b32_e32 v3, 0x3000
	global_atomic_add v3, v4, s[8:9]
	v_mov_b32_e32 v3, 0x3100
	global_atomic_add v3, v4, s[8:9]
	v_mov_b32_e32 v3, 0x3200
	global_atomic_add v3, v4, s[8:9]
	v_mov_b32_e32 v3, 0x3300
	global_atomic_add v3, v4, s[8:9]
	s_branch .Lxb_out_0
.Lxb_wait_0:
	v_mov_b32_e32 v3, 0x2400
	s_mov_b32 s14, 0
.Lxb_spin_0:
	s_sleep 1
	global_load_dword v5, v3, s[38:39] sc1
	s_add_i32 s14, s14, 1
	s_waitcnt vmcnt(0)
	v_cmp_ne_u32_e32 vcc, v5, v1
	s_cbranch_vccnz .Lxb_out_0
	s_and_b32 s15, s14, 0xff
	s_cmp_lg_u32 s15, 0
	s_cbranch_scc1 .Lxb_spin_0
	global_load_dword v5, v10, s[40:41] sc1
	s_waitcnt vmcnt(0)
	v_cmp_ne_u32_e32 vcc, 0, v5
	s_cbranch_vccnz .Lxb_out_0
	s_cmp_lt_u32 s14, 0x40001
	s_cbranch_scc1 .Lxb_spin_0
	global_atomic_add v10, v4, s[40:41]
.Lxb_out_0:
.LBB0_130:
	s_or_b64 exec, exec, s[2:3]
	s_waitcnt lgkmcnt(0)
	s_barrier

; __device__ __forceinline__ unsigned xb_ld(unsigned* p)              { return __hip_atomic_load(p, __ATOMIC_RELAXED, __HIP_MEMORY_SCOPE_AGENT); }
; __device__ __forceinline__ void xcd_barrier_complete(unsigned* bar, unsigned x, unsigned& nloc, unsigned& nx) {
;     const unsigned G = gridDim.x * gridDim.y * gridDim.z;
;     unsigned sum, cnt, mine, sp = 0u;
;     for (;;) {
;         sum = 0u; cnt = 0u; mine = 0u;
; #pragma unroll
;         for (unsigned j = 0; j < 16; ++j) { const unsigned c = xb_ld(&bar[XB_XCNT(j)]); sum += c; cnt += (c > 0u) ? 1u : 0u; mine = (j == x) ? c : mine; }
; __device__ __forceinline__ void xcd_barrier(const XcdBarrier& b) {
;     asm volatile("s_waitcnt vmcnt(0)" ::: "memory");
;     __syncthreads();
;     if (threadIdx.x == 0) {
;         unsigned* bar = b.bar;
;         __builtin_amdgcn_s_waitcnt(0);
;         unsigned nloc = b.st[0], nx = b.st[1];
;         if (nloc == 0u) { xcd_barrier_complete(bar, b.x, nloc, nx); b.st[0] = nloc; b.st[1] = nx; }
.LBB0_148:
	s_cmp_gt_i32 s25, 2
	s_cselect_b64 s[2:3], -1, 0
	s_and_b64 s[0:1], s[0:1], s[2:3]
	s_andn2_b64 vcc, exec, s[0:1]
	s_cbranch_vccnz .LBB0_202
	s_waitcnt vmcnt(0)
	s_waitcnt lgkmcnt(0)
	s_barrier
	s_mov_b64 s[0:1], exec
	v_readlane_b32 s4, v246, 4
	v_readlane_b32 s5, v246, 5
	s_and_b64 s[4:5], s[0:1], s[4:5]
	s_mov_b64 exec, s[4:5]
	s_cbranch_execz .LBB0_201
	s_add_i32 s4, 0, 0x20020
	v_mov_b32_e32 v0, s4
	s_waitcnt vmcnt(0) expcnt(0) lgkmcnt(0)
	buffer_inv sc1
	ds_read_b32 v2, v0
	s_add_i32 s4, 0, 0x20024
	v_mov_b32_e32 v0, s4
	ds_read_b32 v0, v0
	s_waitcnt lgkmcnt(1)
	v_cmp_ne_u32_e32 vcc, 0, v2
	s_cbranch_vccnz .LBB0_165
	v_readlane_b32 s4, v246, 0
	s_mul_i32 s14, s27, s4
	s_add_u32 s4, s22, 0x80200
	s_addc_u32 s5, s23, 0
	s_add_u32 s6, s22, 0x80400
	s_addc_u32 s7, s23, 0
	s_add_u32 s30, s22, 0x80500
	s_addc_u32 s31, s23, 0
	s_add_u32 s34, s22, 0x80600
	s_addc_u32 s35, s23, 0
	s_add_u32 s36, s22, 0x80700
	s_addc_u32 s37, s23, 0
	s_add_u32 s38, s22, 0x80800
	s_addc_u32 s39, s23, 0
	s_add_u32 s40, s22, 0x80900
	s_addc_u32 s41, s23, 0
	s_add_u32 s52, s22, 0x80a00
	s_addc_u32 s53, s23, 0
	s_add_u32 s54, s22, 0x80b00
	s_addc_u32 s55, s23, 0
	s_add_u32 s56, s22, 0x80c00
	s_addc_u32 s57, s23, 0
	s_add_u32 s58, s22, 0x80d00
	s_addc_u32 s59, s23, 0
	s_add_u32 s60, s22, 0x80e00
	s_addc_u32 s61, s23, 0
	s_add_u32 s62, s22, 0x80f00
	s_addc_u32 s63, s23, 0
	s_add_u32 s68, s22, 0x81000
	s_addc_u32 s69, s23, 0
	s_add_u32 s70, s22, 0x81100
	s_addc_u32 s71, s23, 0
	s_add_u32 s72, s22, 0x81200
	s_addc_u32 s73, s23, 0
	s_add_u32 s74, s22, 0x81300
	s_mul_i32 s14, s14, s26
	s_addc_u32 s75, s23, 0
	s_mov_b32 s15, 1
	v_mov_b32_e32 v16, 0
	s_branch .LBB0_153

; __device__ __forceinline__ unsigned xb_ld(unsigned* p)              { return __hip_atomic_load(p, __ATOMIC_RELAXED, __HIP_MEMORY_SCOPE_AGENT); }
; __device__ __forceinline__ unsigned xb_add(unsigned* p, unsigned v) { return __hip_atomic_fetch_add(p, v, __ATOMIC_RELAXED, __HIP_MEMORY_SCOPE_AGENT); }
; #define XB_SPIN(cond, bar) do { unsigned _sp = 0; while (cond) { __builtin_amdgcn_s_sleep(1); \
;     if ((++_sp & 255u) == 0u) { if (xb_ld(&(bar)[XB_TMO])) break; if (_sp > XB_SPIN_CAP) { atomicAdd(&(bar)[XB_TMO], 1u); break; } } } } while (0)
; __device__ __forceinline__ void xcd_barrier(const XcdBarrier& b) {
;     ...
;         const unsigned old = xb_add(&bar[XB_XSUB(b.x)], 1u);
;         const unsigned gen = old / nloc;
;         if (old + 1u == (gen + 1u) * nloc) {
;             __builtin_amdgcn_fence(__ATOMIC_RELEASE, "agent");
;             asm volatile("s_waitcnt vmcnt(0)" ::: "memory");
;             const unsigned og = xb_add(&bar[XB_TOP], 1u);
;             const unsigned tg = og / nx;
;             if (og + 1u == (tg + 1u) * nx) xb_add(&bar[XB_TOPGEN], 1u);
;             else XB_SPIN(xb_ld(&bar[XB_TOPGEN]) == tg, bar);
;             __builtin_amdgcn_fence(__ATOMIC_ACQUIRE, "agent");
;             xb_add(&bar[XB_XGEN(b.x)], 1u);
;             asm volatile("s_waitcnt vmcnt(0)" ::: "memory");
;         } else {
;             XB_SPIN(xb_ld(&bar[XB_XGEN(b.x)]) == gen, bar);
;             __builtin_amdgcn_fence(__ATOMIC_ACQUIRE, "agent");
;             asm volatile("s_waitcnt vmcnt(0)" ::: "memory");
;         }
.Lxb_out_1:
.LBB0_201:
	s_or_b64 exec, exec, s[0:1]
	s_waitcnt lgkmcnt(0)
	s_barrier

; __device__ __forceinline__ unsigned xb_ld(unsigned* p)              { return __hip_atomic_load(p, __ATOMIC_RELAXED, __HIP_MEMORY_SCOPE_AGENT); }
; __device__ __forceinline__ void xcd_barrier_complete(unsigned* bar, unsigned x, unsigned& nloc, unsigned& nx) {
;     const unsigned G = gridDim.x * gridDim.y * gridDim.z;
;     unsigned sum, cnt, mine, sp = 0u;
;     for (;;) {
;         sum = 0u; cnt = 0u; mine = 0u;
; #pragma unroll
;         for (unsigned j = 0; j < 16; ++j) { const unsigned c = xb_ld(&bar[XB_XCNT(j)]); sum += c; cnt += (c > 0u) ? 1u : 0u; mine = (j == x) ? c : mine; }
; __device__ __forceinline__ void xcd_barrier(const XcdBarrier& b) {
;     asm volatile("s_waitcnt vmcnt(0)" ::: "memory");
;     __syncthreads();
;     if (threadIdx.x == 0) {
;         unsigned* bar = b.bar;
;         __builtin_amdgcn_s_waitcnt(0);
;         unsigned nloc = b.st[0], nx = b.st[1];
;         if (nloc == 0u) { xcd_barrier_complete(bar, b.x, nloc, nx); b.st[0] = nloc; b.st[1] = nx; }
.LBB0_249:
	s_cmp_gt_i32 s25, 3
	s_cselect_b64 s[0:1], -1, 0
	s_and_b64 s[2:3], s[6:7], s[0:1]
	s_andn2_b64 vcc, exec, s[2:3]
	s_cbranch_vccnz .LBB0_303
	s_waitcnt vmcnt(0)
	s_waitcnt lgkmcnt(0)
	s_barrier
	s_mov_b64 s[2:3], exec
	v_readlane_b32 s4, v246, 4
	v_readlane_b32 s5, v246, 5
	s_and_b64 s[4:5], s[2:3], s[4:5]
	s_mov_b64 exec, s[4:5]
	s_cbranch_execz .LBB0_302
	s_add_i32 s4, 0, 0x20020
	v_mov_b32_e32 v0, s4
	s_waitcnt vmcnt(0) expcnt(0) lgkmcnt(0)
	buffer_inv sc1
	ds_read_b32 v2, v0
	s_add_i32 s4, 0, 0x20024
	v_mov_b32_e32 v0, s4
	ds_read_b32 v0, v0
	s_waitcnt lgkmcnt(1)
	v_cmp_ne_u32_e32 vcc, 0, v2
	s_cbranch_vccnz .LBB0_266
	v_readlane_b32 s4, v246, 0
	s_mul_i32 s14, s27, s4
	s_add_u32 s4, s22, 0x80200
	s_addc_u32 s5, s23, 0
	s_add_u32 s6, s22, 0x80400
	s_addc_u32 s7, s23, 0
	s_add_u32 s30, s22, 0x80500
	s_addc_u32 s31, s23, 0
	s_add_u32 s34, s22, 0x80600
	s_addc_u32 s35, s23, 0
	s_add_u32 s36, s22, 0x80700
	s_addc_u32 s37, s23, 0
	s_add_u32 s38, s22, 0x80800
	s_addc_u32 s39, s23, 0
	s_add_u32 s40, s22, 0x80900
	s_addc_u32 s41, s23, 0
	s_add_u32 s52, s22, 0x80a00
	s_addc_u32 s53, s23, 0
	s_add_u32 s54, s22, 0x80b00
	s_addc_u32 s55, s23, 0
	s_add_u32 s56, s22, 0x80c00
	s_addc_u32 s57, s23, 0
	s_add_u32 s58, s22, 0x80d00
	s_addc_u32 s59, s23, 0
	s_add_u32 s60, s22, 0x80e00
	s_addc_u32 s61, s23, 0
	s_add_u32 s62, s22, 0x80f00
	s_addc_u32 s63, s23, 0
	s_add_u32 s68, s22, 0x81000
	s_addc_u32 s69, s23, 0
	s_add_u32 s70, s22, 0x81100
	s_addc_u32 s71, s23, 0
	s_add_u32 s72, s22, 0x81200
	s_addc_u32 s73, s23, 0
	s_add_u32 s74, s22, 0x81300
	s_mul_i32 s14, s14, s26
	s_addc_u32 s75, s23, 0
	s_mov_b32 s15, 1
	v_mov_b32_e32 v16, 0
	s_branch .LBB0_254

; __device__ __forceinline__ unsigned xb_ld(unsigned* p)              { return __hip_atomic_load(p, __ATOMIC_RELAXED, __HIP_MEMORY_SCOPE_AGENT); }
; __device__ __forceinline__ void xcd_barrier_complete(unsigned* bar, unsigned x, unsigned& nloc, unsigned& nx) {
;     const unsigned G = gridDim.x * gridDim.y * gridDim.z;
;     unsigned sum, cnt, mine, sp = 0u;
;     for (;;) {
;         sum = 0u; cnt = 0u; mine = 0u;
; #pragma unroll
;         for (unsigned j = 0; j < 16; ++j) { const unsigned c = xb_ld(&bar[XB_XCNT(j)]); sum += c; cnt += (c > 0u) ? 1u : 0u; mine = (j == x) ? c : mine; }
; __device__ __forceinline__ void xcd_barrier(const XcdBarrier& b) {
;     asm volatile("s_waitcnt vmcnt(0)" ::: "memory");
;     __syncthreads();
;     if (threadIdx.x == 0) {
;         unsigned* bar = b.bar;
;         __builtin_amdgcn_s_waitcnt(0);
;         unsigned nloc = b.st[0], nx = b.st[1];
;         if (nloc == 0u) { xcd_barrier_complete(bar, b.x, nloc, nx); b.st[0] = nloc; b.st[1] = nx; }
.LBB0_432:
	s_cmp_gt_i32 s25, 4
	s_cselect_b64 s[2:3], -1, 0
	s_and_b64 s[0:1], s[0:1], s[2:3]
	s_andn2_b64 vcc, exec, s[0:1]
	s_cbranch_vccnz .LBB0_486
	s_waitcnt vmcnt(0)
	s_waitcnt lgkmcnt(0)
	s_barrier
	s_mov_b64 s[0:1], exec
	v_readlane_b32 s4, v246, 4
	v_readlane_b32 s5, v246, 5
	s_and_b64 s[4:5], s[0:1], s[4:5]
	s_mov_b64 exec, s[4:5]
	s_cbranch_execz .LBB0_485
	s_add_i32 s4, 0, 0x20020
	v_mov_b32_e32 v0, s4
	s_waitcnt vmcnt(0) expcnt(0) lgkmcnt(0)
	buffer_inv sc1
	ds_read_b32 v2, v0
	s_add_i32 s4, 0, 0x20024
	v_mov_b32_e32 v0, s4
	ds_read_b32 v0, v0
	s_waitcnt lgkmcnt(1)
	v_cmp_ne_u32_e32 vcc, 0, v2
	s_cbranch_vccnz .LBB0_449
	v_readlane_b32 s4, v246, 0
	s_mul_i32 s14, s27, s4
	s_add_u32 s4, s22, 0x80200
	s_addc_u32 s5, s23, 0
	s_add_u32 s6, s22, 0x80400
	s_addc_u32 s7, s23, 0
	s_add_u32 s10, s22, 0x80500
	s_addc_u32 s11, s23, 0
	s_add_u32 s30, s22, 0x80600
	s_addc_u32 s31, s23, 0
	s_add_u32 s34, s22, 0x80700
	s_addc_u32 s35, s23, 0
	s_add_u32 s36, s22, 0x80800
	s_addc_u32 s37, s23, 0
	s_add_u32 s38, s22, 0x80900
	s_addc_u32 s39, s23, 0
	s_add_u32 s40, s22, 0x80a00
	s_addc_u32 s41, s23, 0
	s_add_u32 s42, s22, 0x80b00
	s_addc_u32 s43, s23, 0
	s_add_u32 s44, s22, 0x80c00
	s_addc_u32 s45, s23, 0
	s_add_u32 s46, s22, 0x80d00
	s_addc_u32 s47, s23, 0
	s_add_u32 s48, s22, 0x80e00
	s_addc_u32 s49, s23, 0
	s_add_u32 s52, s22, 0x80f00
	s_addc_u32 s53, s23, 0
	s_add_u32 s54, s22, 0x81000
	s_addc_u32 s55, s23, 0
	s_add_u32 s56, s22, 0x81100
	s_addc_u32 s57, s23, 0
	s_add_u32 s58, s22, 0x81200
	s_addc_u32 s59, s23, 0
	s_add_u32 s60, s22, 0x81300
	s_mul_i32 s14, s14, s26
	s_addc_u32 s61, s23, 0
	s_mov_b32 s15, 1
	v_mov_b32_e32 v16, 0
	s_branch .LBB0_437

; __device__ __forceinline__ unsigned xb_ld(unsigned* p)              { return __hip_atomic_load(p, __ATOMIC_RELAXED, __HIP_MEMORY_SCOPE_AGENT); }
; __device__ __forceinline__ void xcd_barrier_complete(unsigned* bar, unsigned x, unsigned& nloc, unsigned& nx) {
;     const unsigned G = gridDim.x * gridDim.y * gridDim.z;
;     unsigned sum, cnt, mine, sp = 0u;
;     for (;;) {
;         sum = 0u; cnt = 0u; mine = 0u;
; #pragma unroll
;         for (unsigned j = 0; j < 16; ++j) { const unsigned c = xb_ld(&bar[XB_XCNT(j)]); sum += c; cnt += (c > 0u) ? 1u : 0u; mine = (j == x) ? c : mine; }
; __device__ __forceinline__ void xcd_barrier(const XcdBarrier& b) {
;     asm volatile("s_waitcnt vmcnt(0)" ::: "memory");
;     __syncthreads();
;     if (threadIdx.x == 0) {
;         unsigned* bar = b.bar;
;         __builtin_amdgcn_s_waitcnt(0);
;         unsigned nloc = b.st[0], nx = b.st[1];
;         if (nloc == 0u) { xcd_barrier_complete(bar, b.x, nloc, nx); b.st[0] = nloc; b.st[1] = nx; }
.LBB0_572:
	s_cmp_gt_i32 s25, 5
	s_cselect_b64 s[2:3], -1, 0
	s_and_b64 s[0:1], s[0:1], s[2:3]
	s_andn2_b64 vcc, exec, s[0:1]
	s_cbranch_vccnz .LBB0_626
	s_waitcnt vmcnt(0)
	s_waitcnt lgkmcnt(0)
	s_barrier
	s_mov_b64 s[0:1], exec
	v_readlane_b32 s4, v246, 4
	v_readlane_b32 s5, v246, 5
	s_and_b64 s[4:5], s[0:1], s[4:5]
	s_mov_b64 exec, s[4:5]
	s_cbranch_execz .LBB0_625
	s_add_i32 s4, 0, 0x20020
	v_mov_b32_e32 v0, s4
	s_waitcnt vmcnt(0) expcnt(0) lgkmcnt(0)
	buffer_inv sc1
	ds_read_b32 v2, v0
	s_add_i32 s4, 0, 0x20024
	v_mov_b32_e32 v0, s4
	ds_read_b32 v0, v0
	s_waitcnt lgkmcnt(1)
	v_cmp_ne_u32_e32 vcc, 0, v2
	s_cbranch_vccnz .LBB0_589
	v_readlane_b32 s4, v246, 0
	s_mul_i32 s14, s27, s4
	s_add_u32 s4, s22, 0x80200
	s_addc_u32 s5, s23, 0
	s_add_u32 s6, s22, 0x80400
	s_addc_u32 s7, s23, 0
	s_add_u32 s10, s22, 0x80500
	s_addc_u32 s11, s23, 0
	s_add_u32 s34, s22, 0x80600
	s_addc_u32 s35, s23, 0
	s_add_u32 s36, s22, 0x80700
	s_addc_u32 s37, s23, 0
	s_add_u32 s38, s22, 0x80800
	s_addc_u32 s39, s23, 0
	s_add_u32 s40, s22, 0x80900
	s_addc_u32 s41, s23, 0
	s_add_u32 s42, s22, 0x80a00
	s_addc_u32 s43, s23, 0
	s_add_u32 s44, s22, 0x80b00
	s_addc_u32 s45, s23, 0
	s_add_u32 s46, s22, 0x80c00
	s_addc_u32 s47, s23, 0
	s_add_u32 s48, s22, 0x80d00
	s_addc_u32 s49, s23, 0
	s_add_u32 s52, s22, 0x80e00
	s_addc_u32 s53, s23, 0
	s_add_u32 s54, s22, 0x80f00
	s_addc_u32 s55, s23, 0
	s_add_u32 s56, s22, 0x81000
	s_addc_u32 s57, s23, 0
	s_add_u32 s58, s22, 0x81100
	s_addc_u32 s59, s23, 0
	s_add_u32 s60, s22, 0x81200
	s_addc_u32 s61, s23, 0
	s_add_u32 s62, s22, 0x81300
	s_mul_i32 s14, s14, s26
	s_addc_u32 s63, s23, 0
	s_mov_b32 s15, 1
	v_mov_b32_e32 v16, 0
	s_branch .LBB0_577

; __device__ __forceinline__ unsigned xb_ld(unsigned* p)              { return __hip_atomic_load(p, __ATOMIC_RELAXED, __HIP_MEMORY_SCOPE_AGENT); }
; __device__ __forceinline__ void xcd_barrier_complete(unsigned* bar, unsigned x, unsigned& nloc, unsigned& nx) {
;     const unsigned G = gridDim.x * gridDim.y * gridDim.z;
;     unsigned sum, cnt, mine, sp = 0u;
;     for (;;) {
;         sum = 0u; cnt = 0u; mine = 0u;
; #pragma unroll
;         for (unsigned j = 0; j < 16; ++j) { const unsigned c = xb_ld(&bar[XB_XCNT(j)]); sum += c; cnt += (c > 0u) ? 1u : 0u; mine = (j == x) ? c : mine; }
; __device__ __forceinline__ void xcd_barrier(const XcdBarrier& b) {
;     asm volatile("s_waitcnt vmcnt(0)" ::: "memory");
;     __syncthreads();
;     if (threadIdx.x == 0) {
;         unsigned* bar = b.bar;
;         __builtin_amdgcn_s_waitcnt(0);
;         unsigned nloc = b.st[0], nx = b.st[1];
;         if (nloc == 0u) { xcd_barrier_complete(bar, b.x, nloc, nx); b.st[0] = nloc; b.st[1] = nx; }
.LBB0_677:
	s_cmp_gt_i32 s25, 6
	s_cselect_b64 s[2:3], -1, 0
	s_and_b64 s[0:1], s[4:5], s[2:3]
	s_andn2_b64 vcc, exec, s[0:1]
	s_cbranch_vccnz .LBB0_731
	s_waitcnt vmcnt(0)
	s_waitcnt lgkmcnt(0)
	s_barrier
	s_mov_b64 s[0:1], exec
	v_readlane_b32 s4, v246, 4
	v_readlane_b32 s5, v246, 5
	s_and_b64 s[4:5], s[0:1], s[4:5]
	s_mov_b64 exec, s[4:5]
	s_cbranch_execz .LBB0_730
	s_add_i32 s4, 0, 0x20020
	v_mov_b32_e32 v0, s4
	s_waitcnt vmcnt(0) expcnt(0) lgkmcnt(0)
	buffer_inv sc1
	ds_read_b32 v2, v0
	s_add_i32 s4, 0, 0x20024
	v_mov_b32_e32 v0, s4
	ds_read_b32 v0, v0
	s_waitcnt lgkmcnt(1)
	v_cmp_ne_u32_e32 vcc, 0, v2
	s_cbranch_vccnz .LBB0_694
	v_readlane_b32 s4, v246, 0
	s_mul_i32 s14, s27, s4
	s_add_u32 s4, s22, 0x80200
	s_addc_u32 s5, s23, 0
	s_add_u32 s8, s22, 0x80400
	s_addc_u32 s9, s23, 0
	s_add_u32 s10, s22, 0x80500
	s_addc_u32 s11, s23, 0
	s_add_u32 s34, s22, 0x80600
	s_addc_u32 s35, s23, 0
	s_add_u32 s36, s22, 0x80700
	s_addc_u32 s37, s23, 0
	s_add_u32 s38, s22, 0x80800
	s_addc_u32 s39, s23, 0
	s_add_u32 s40, s22, 0x80900
	s_addc_u32 s41, s23, 0
	s_add_u32 s42, s22, 0x80a00
	s_addc_u32 s43, s23, 0
	s_add_u32 s44, s22, 0x80b00
	s_addc_u32 s45, s23, 0
	s_add_u32 s46, s22, 0x80c00
	s_addc_u32 s47, s23, 0
	s_add_u32 s48, s22, 0x80d00
	s_addc_u32 s49, s23, 0
	s_add_u32 s52, s22, 0x80e00
	s_addc_u32 s53, s23, 0
	s_add_u32 s54, s22, 0x80f00
	s_addc_u32 s55, s23, 0
	s_add_u32 s56, s22, 0x81000
	s_addc_u32 s57, s23, 0
	s_add_u32 s58, s22, 0x81100
	s_addc_u32 s59, s23, 0
	s_add_u32 s60, s22, 0x81200
	s_addc_u32 s61, s23, 0
	s_add_u32 s62, s22, 0x81300
	s_mul_i32 s14, s14, s26
	s_addc_u32 s63, s23, 0
	s_mov_b32 s15, 1
	v_mov_b32_e32 v16, 0
	s_branch .LBB0_682

; __device__ __forceinline__ unsigned xb_ld(unsigned* p)              { return __hip_atomic_load(p, __ATOMIC_RELAXED, __HIP_MEMORY_SCOPE_AGENT); }
; __device__ __forceinline__ void xcd_barrier_complete(unsigned* bar, unsigned x, unsigned& nloc, unsigned& nx) {
;     const unsigned G = gridDim.x * gridDim.y * gridDim.z;
;     unsigned sum, cnt, mine, sp = 0u;
;     for (;;) {
;         sum = 0u; cnt = 0u; mine = 0u;
; #pragma unroll
;         for (unsigned j = 0; j < 16; ++j) { const unsigned c = xb_ld(&bar[XB_XCNT(j)]); sum += c; cnt += (c > 0u) ? 1u : 0u; mine = (j == x) ? c : mine; }
; __device__ __forceinline__ void xcd_barrier(const XcdBarrier& b) {
;     asm volatile("s_waitcnt vmcnt(0)" ::: "memory");
;     __syncthreads();
;     if (threadIdx.x == 0) {
;         unsigned* bar = b.bar;
;         __builtin_amdgcn_s_waitcnt(0);
;         unsigned nloc = b.st[0], nx = b.st[1];
;         if (nloc == 0u) { xcd_barrier_complete(bar, b.x, nloc, nx); b.st[0] = nloc; b.st[1] = nx; }
.LBB0_774:
	s_cmp_gt_i32 s25, 7
	s_cselect_b64 s[2:3], -1, 0
	s_and_b64 s[4:5], s[8:9], s[2:3]
	s_andn2_b64 vcc, exec, s[4:5]
	s_cbranch_vccnz .LBB0_828
	s_waitcnt vmcnt(0)
	s_waitcnt lgkmcnt(0)
	s_barrier
	s_mov_b64 s[4:5], exec
	v_readlane_b32 s6, v246, 4
	v_readlane_b32 s7, v246, 5
	s_and_b64 s[6:7], s[4:5], s[6:7]
	s_mov_b64 exec, s[6:7]
	s_cbranch_execz .LBB0_827
	s_add_i32 s6, 0, 0x20020
	v_mov_b32_e32 v0, s6
	s_waitcnt vmcnt(0) expcnt(0) lgkmcnt(0)
	buffer_inv sc1
	ds_read_b32 v2, v0
	s_add_i32 s6, 0, 0x20024
	v_mov_b32_e32 v0, s6
	ds_read_b32 v0, v0
	s_waitcnt lgkmcnt(1)
	v_cmp_ne_u32_e32 vcc, 0, v2
	s_cbranch_vccnz .LBB0_791
	v_readlane_b32 s6, v246, 0
	s_mul_i32 s14, s27, s6
	s_add_u32 s6, s22, 0x80200
	s_addc_u32 s7, s23, 0
	s_add_u32 s8, s22, 0x80400
	s_addc_u32 s9, s23, 0
	s_add_u32 s10, s22, 0x80500
	s_addc_u32 s11, s23, 0
	s_add_u32 s34, s22, 0x80600
	s_addc_u32 s35, s23, 0
	s_add_u32 s36, s22, 0x80700
	s_addc_u32 s37, s23, 0
	s_add_u32 s38, s22, 0x80800
	s_addc_u32 s39, s23, 0
	s_add_u32 s40, s22, 0x80900
	s_addc_u32 s41, s23, 0
	s_add_u32 s42, s22, 0x80a00
	s_addc_u32 s43, s23, 0
	s_add_u32 s44, s22, 0x80b00
	s_addc_u32 s45, s23, 0
	s_add_u32 s46, s22, 0x80c00
	s_addc_u32 s47, s23, 0
	s_add_u32 s48, s22, 0x80d00
	s_addc_u32 s49, s23, 0
	s_add_u32 s52, s22, 0x80e00
	s_addc_u32 s53, s23, 0
	s_add_u32 s54, s22, 0x80f00
	s_addc_u32 s55, s23, 0
	s_add_u32 s56, s22, 0x81000
	s_addc_u32 s57, s23, 0
	s_add_u32 s58, s22, 0x81100
	s_addc_u32 s59, s23, 0
	s_add_u32 s60, s22, 0x81200
	s_addc_u32 s61, s23, 0
	s_add_u32 s62, s22, 0x81300
	s_mul_i32 s14, s14, s26
	s_addc_u32 s63, s23, 0
	s_mov_b32 s15, 1
	v_mov_b32_e32 v16, 0
	s_branch .LBB0_779

; __device__ __forceinline__ unsigned xb_ld(unsigned* p)              { return __hip_atomic_load(p, __ATOMIC_RELAXED, __HIP_MEMORY_SCOPE_AGENT); }
; __device__ __forceinline__ unsigned xb_add(unsigned* p, unsigned v) { return __hip_atomic_fetch_add(p, v, __ATOMIC_RELAXED, __HIP_MEMORY_SCOPE_AGENT); }
; #define XB_SPIN(cond, bar) do { unsigned _sp = 0; while (cond) { __builtin_amdgcn_s_sleep(1); \
;     if ((++_sp & 255u) == 0u) { if (xb_ld(&(bar)[XB_TMO])) break; if (_sp > XB_SPIN_CAP) { atomicAdd(&(bar)[XB_TMO], 1u); break; } } } } while (0)
; __device__ __forceinline__ void xcd_barrier(const XcdBarrier& b) {
;     ...
;         const unsigned old = xb_add(&bar[XB_XSUB(b.x)], 1u);
;         const unsigned gen = old / nloc;
;         if (old + 1u == (gen + 1u) * nloc) {
;             __builtin_amdgcn_fence(__ATOMIC_RELEASE, "agent");
;             asm volatile("s_waitcnt vmcnt(0)" ::: "memory");
;             const unsigned og = xb_add(&bar[XB_TOP], 1u);
;             const unsigned tg = og / nx;
;             if (og + 1u == (tg + 1u) * nx) xb_add(&bar[XB_TOPGEN], 1u);
;             else XB_SPIN(xb_ld(&bar[XB_TOPGEN]) == tg, bar);
;             __builtin_amdgcn_fence(__ATOMIC_ACQUIRE, "agent");
;             xb_add(&bar[XB_XGEN(b.x)], 1u);
;             asm volatile("s_waitcnt vmcnt(0)" ::: "memory");
;         } else {
;             XB_SPIN(xb_ld(&bar[XB_XGEN(b.x)]) == gen, bar);
;             __builtin_amdgcn_fence(__ATOMIC_ACQUIRE, "agent");
;             asm volatile("s_waitcnt vmcnt(0)" ::: "memory");
;         }
.Lxb_out_6:
.LBB0_827:
	s_or_b64 exec, exec, s[4:5]
	s_waitcnt lgkmcnt(0)
	s_barrier

; __device__ __forceinline__ unsigned xb_ld(unsigned* p)              { return __hip_atomic_load(p, __ATOMIC_RELAXED, __HIP_MEMORY_SCOPE_AGENT); }
; __device__ __forceinline__ void xcd_barrier_complete(unsigned* bar, unsigned x, unsigned& nloc, unsigned& nx) {
;     const unsigned G = gridDim.x * gridDim.y * gridDim.z;
;     unsigned sum, cnt, mine, sp = 0u;
;     for (;;) {
;         sum = 0u; cnt = 0u; mine = 0u;
; #pragma unroll
;         for (unsigned j = 0; j < 16; ++j) { const unsigned c = xb_ld(&bar[XB_XCNT(j)]); sum += c; cnt += (c > 0u) ? 1u : 0u; mine = (j == x) ? c : mine; }
; __device__ __forceinline__ void xcd_barrier(const XcdBarrier& b) {
;     asm volatile("s_waitcnt vmcnt(0)" ::: "memory");
;     __syncthreads();
;     if (threadIdx.x == 0) {
;         unsigned* bar = b.bar;
;         __builtin_amdgcn_s_waitcnt(0);
;         unsigned nloc = b.st[0], nx = b.st[1];
;         if (nloc == 0u) { xcd_barrier_complete(bar, b.x, nloc, nx); b.st[0] = nloc; b.st[1] = nx; }
.LBB0_845:
	s_cmp_gt_i32 s25, 8
	s_cselect_b64 s[0:1], -1, 0
	s_and_b64 s[2:3], s[4:5], s[0:1]
	s_andn2_b64 vcc, exec, s[2:3]
	s_cbranch_vccnz .LBB0_899
	s_waitcnt vmcnt(0)
	s_waitcnt lgkmcnt(0)
	s_barrier
	s_mov_b64 s[2:3], exec
	v_readlane_b32 s4, v246, 4
	v_readlane_b32 s5, v246, 5
	s_and_b64 s[4:5], s[2:3], s[4:5]
	s_mov_b64 exec, s[4:5]
	s_cbranch_execz .LBB0_898
	s_add_i32 s4, 0, 0x20020
	v_mov_b32_e32 v0, s4
	s_waitcnt vmcnt(0) expcnt(0) lgkmcnt(0)
	buffer_inv sc1
	ds_read_b32 v2, v0
	s_add_i32 s4, 0, 0x20024
	v_mov_b32_e32 v0, s4
	ds_read_b32 v0, v0
	s_waitcnt lgkmcnt(1)
	v_cmp_ne_u32_e32 vcc, 0, v2
	s_cbranch_vccnz .LBB0_862
	v_readlane_b32 s4, v246, 0
	s_mul_i32 s14, s27, s4
	s_add_u32 s4, s22, 0x80200
	s_addc_u32 s5, s23, 0
	s_add_u32 s6, s22, 0x80400
	s_addc_u32 s7, s23, 0
	s_add_u32 s8, s22, 0x80500
	s_addc_u32 s9, s23, 0
	s_add_u32 s10, s22, 0x80600
	s_addc_u32 s11, s23, 0
	s_add_u32 s34, s22, 0x80700
	s_addc_u32 s35, s23, 0
	s_add_u32 s36, s22, 0x80800
	s_addc_u32 s37, s23, 0
	s_add_u32 s38, s22, 0x80900
	s_addc_u32 s39, s23, 0
	s_add_u32 s40, s22, 0x80a00
	s_addc_u32 s41, s23, 0
	s_add_u32 s42, s22, 0x80b00
	s_addc_u32 s43, s23, 0
	s_add_u32 s44, s22, 0x80c00
	s_addc_u32 s45, s23, 0
	s_add_u32 s46, s22, 0x80d00
	s_addc_u32 s47, s23, 0
	s_add_u32 s48, s22, 0x80e00
	s_addc_u32 s49, s23, 0
	s_add_u32 s52, s22, 0x80f00
	s_addc_u32 s53, s23, 0
	s_add_u32 s54, s22, 0x81000
	s_addc_u32 s55, s23, 0
	s_add_u32 s56, s22, 0x81100
	s_addc_u32 s57, s23, 0
	s_add_u32 s58, s22, 0x81200
	s_addc_u32 s59, s23, 0
	s_add_u32 s60, s22, 0x81300
	s_mul_i32 s14, s14, s26
	s_addc_u32 s61, s23, 0
	s_mov_b32 s15, 1
	v_mov_b32_e32 v16, 0
	s_branch .LBB0_850
